# t12 + P5 score waves: the 4 K tile DMAs issued at the step head (right after the first K fragment reads) instead of behind MFMAs 2,4,6,8
# speedup vs baseline: 1.0238x; 1.0238x over previous
; __device__ __forceinline__ void partialSM(f32x16& p0, f32x16& p1, float& m_reg, float& mn, float& alpha) {
;   constexpr float C = SCALE * L2E;
;   float pmax = p0[0];
; #pragma unroll
;   for (int r = 1; r < 16; ++r) pmax = fmaxf(pmax, p0[r]);
; #pragma unroll
;   for (int r = 0; r < 16; ++r) pmax = fmaxf(pmax, p1[r]);
;   { auto rr = __builtin_amdgcn_permlane32_swap(__float_as_uint(pmax), __float_as_uint(pmax), false, false);
;     pmax = fmaxf(__uint_as_float(rr[0]), __uint_as_float(rr[1])); }
;   if (__builtin_expect(__all(pmax - m_reg <= THR / SCALE), 1)) { mn = m_reg; alpha = 1.f; }
;   else { mn = fmaxf(m_reg, pmax); alpha = __builtin_amdgcn_exp2f((m_reg - mn) * C); m_reg = mn; }
;   float mnC = -mn * C;
; #pragma unroll
;   for (int r = 0; r < 16; ++r) p0[r] = fmaf(p0[r], C, mnC);
; #pragma unroll
;   for (int r = 0; r < 16; ++r) p1[r] = fmaf(p1[r], C, mnC);
; #pragma unroll
;   for (int r = 0; r < 16; ++r) p0[r] = __builtin_amdgcn_exp2f(p0[r]);
; }
; __device__ __forceinline__ void finishSM(f32x16& p0, f32x16& p1, float alpha, float& l_reg, bf16x8& pa0, bf16x8& pa1, bf16x8& pa2, bf16x8& pa3) {
; #pragma unroll
;   for (int r = 0; r < 16; ++r) p1[r] = __builtin_amdgcn_exp2f(p1[r]);
;   float ps = 0;
; #pragma unroll
;   for (int r = 0; r < 16; ++r) ps += p0[r];
; #pragma unroll
;   for (int r = 0; r < 16; ++r) ps += p1[r];
;   { auto rr = __builtin_amdgcn_permlane32_swap(__float_as_uint(ps), __float_as_uint(ps), false, false);
;     ps = __uint_as_float(rr[0]) + __uint_as_float(rr[1]); }
;   l_reg = l_reg * alpha + ps;
.LBB0_508:
	s_cmpk_gt_u32 s71, 0x7d
	s_cselect_b64 s[48:49], -1, 0
	s_add_i32 s8, s72, 0xffffe000
	s_cmpk_lt_u32 s71, 0x7e
	s_cselect_b32 s8, s8, 0xfe000
	s_lshl_b64 s[84:85], s[8:9], 1
	s_add_u32 s84, s46, s84
	s_addc_u32 s85, s47, s85
	ds_read_b128 v[200:203], v108
	ds_read_b128 v[204:207], v108 offset:8192
	ds_read_b128 v[208:211], v109
	ds_read_b128 v[212:215], v109 offset:8192
	ds_read_b128 v[216:219], v110
	ds_read_b128 v[220:223], v110 offset:8192
	ds_read_b128 v[224:227], v111
	ds_read_b128 v[228:231], v111 offset:8192
	s_mov_b32 m0, s64
	s_nop 0
	global_load_lds_dwordx4 v0, s[84:85]
	s_mov_b32 m0, s2
	s_nop 0
	global_load_lds_dwordx4 v236, s[84:85]
	s_mov_b32 m0, s3
	s_nop 0
	global_load_lds_dwordx4 v237, s[84:85]
	s_mov_b32 m0, s66
	s_nop 0
	global_load_lds_dwordx4 v238, s[84:85]
	v_max_f32_e32 v99, v19, v19
	v_max_f32_e32 v118, v18, v18
	v_max_f32_e32 v99, v118, v99
	v_max3_f32 v99, v99, v20, v21
	v_max3_f32 v99, v99, v22, v23
	v_max3_f32 v99, v99, v24, v25
	v_max3_f32 v99, v99, v26, v27
	v_max3_f32 v99, v99, v28, v29
	v_max3_f32 v99, v99, v30, v31
	v_max3_f32 v99, v99, v32, v33
	s_waitcnt lgkmcnt(6)
	v_mfma_f32_32x32x16_bf16 v[50:65], v[200:203], v[66:69], 0
	v_max3_f32 v99, v99, v2, v3
	v_max3_f32 v99, v99, v4, v5
	v_max3_f32 v99, v99, v6, v7
	v_max3_f32 v99, v99, v8, v9
	v_max3_f32 v99, v99, v10, v11
	v_max3_f32 v99, v99, v12, v13
	v_max3_f32 v99, v99, v14, v15
	v_max3_f32 v99, v99, v16, v17
	v_mov_b32_e32 v118, v99
	v_mfma_f32_32x32x16_bf16 v[34:49], v[204:207], v[66:69], 0
	ds_read_b128 v[200:203], v113
	ds_read_b128 v[204:207], v113 offset:8192
	s_nop 1
	v_permlane32_swap_b32_e32 v99, v118
	v_max_f32_e32 v118, v118, v118
	v_max_f32_e32 v99, v99, v99
	v_max_f32_e32 v99, v99, v118
	v_sub_f32_e32 v118, v99, v121
	v_cmp_ge_f32_e32 vcc, s61, v118
	v_max_f32_e32 v119, v121, v121
	s_cmp_eq_u64 vcc, exec
	v_max_f32_e32 v99, v119, v99
	s_cselect_b64 vcc, -1, 0
	s_waitcnt lgkmcnt(6)
	v_mfma_f32_32x32x16_bf16 v[50:65], v[208:211], v[70:73], v[50:65]
	v_sub_f32_e32 v119, v121, v99
	v_cndmask_b32_e32 v121, v99, v121, vcc
	v_mul_f32_e32 v99, 0xbe0293ee, v121
	v_fmamk_f32 v18, v18, 0x3e0293ee, v99
	v_fmamk_f32 v19, v19, 0x3e0293ee, v99
	v_fmamk_f32 v20, v20, 0x3e0293ee, v99
	v_fmamk_f32 v21, v21, 0x3e0293ee, v99
	v_fmamk_f32 v22, v22, 0x3e0293ee, v99
	v_mfma_f32_32x32x16_bf16 v[34:49], v[212:215], v[70:73], v[34:49]
	ds_read_b128 v[208:211], v114
	ds_read_b128 v[212:215], v114 offset:8192
	v_fmamk_f32 v23, v23, 0x3e0293ee, v99
	v_fmamk_f32 v24, v24, 0x3e0293ee, v99
	v_fmamk_f32 v25, v25, 0x3e0293ee, v99
	v_fmamk_f32 v26, v26, 0x3e0293ee, v99
	v_fmamk_f32 v27, v27, 0x3e0293ee, v99
	v_fmamk_f32 v28, v28, 0x3e0293ee, v99
	v_fmamk_f32 v29, v29, 0x3e0293ee, v99
	v_fmamk_f32 v30, v30, 0x3e0293ee, v99
	v_fmamk_f32 v31, v31, 0x3e0293ee, v99
	s_waitcnt lgkmcnt(6)
	v_mfma_f32_32x32x16_bf16 v[50:65], v[216:219], v[74:77], v[50:65]
	v_fmamk_f32 v32, v32, 0x3e0293ee, v99
	v_fmamk_f32 v33, v33, 0x3e0293ee, v99
	v_fmamk_f32 v2, v2, 0x3e0293ee, v99
	v_fmamk_f32 v3, v3, 0x3e0293ee, v99
	v_fmamk_f32 v4, v4, 0x3e0293ee, v99
	v_fmamk_f32 v5, v5, 0x3e0293ee, v99
	v_fmamk_f32 v6, v6, 0x3e0293ee, v99
	v_fmamk_f32 v7, v7, 0x3e0293ee, v99
	v_fmamk_f32 v8, v8, 0x3e0293ee, v99
	v_mfma_f32_32x32x16_bf16 v[34:49], v[220:223], v[74:77], v[34:49]
	ds_read_b128 v[216:219], v115
	ds_read_b128 v[220:223], v115 offset:8192
	v_fmamk_f32 v9, v9, 0x3e0293ee, v99
	v_fmamk_f32 v10, v10, 0x3e0293ee, v99
	v_fmamk_f32 v11, v11, 0x3e0293ee, v99
	v_fmamk_f32 v12, v12, 0x3e0293ee, v99
	v_fmamk_f32 v13, v13, 0x3e0293ee, v99
	v_fmamk_f32 v14, v14, 0x3e0293ee, v99
	v_fmamk_f32 v15, v15, 0x3e0293ee, v99
	v_fmamk_f32 v16, v16, 0x3e0293ee, v99
	v_fmac_f32_e32 v99, 0x3e0293ee, v17
	v_exp_f32_e32 v17, v18
	s_waitcnt lgkmcnt(6)
	v_mfma_f32_32x32x16_bf16 v[50:65], v[224:227], v[78:81], v[50:65]
	v_exp_f32_e32 v18, v19
	v_exp_f32_e32 v19, v20
	v_exp_f32_e32 v20, v21
	v_exp_f32_e32 v21, v22
	v_exp_f32_e32 v22, v23
	v_exp_f32_e32 v23, v24
	v_exp_f32_e32 v24, v25
	v_exp_f32_e32 v25, v26
	v_exp_f32_e32 v26, v27
	v_mfma_f32_32x32x16_bf16 v[34:49], v[228:231], v[78:81], v[34:49]
	ds_read_b128 v[224:227], v116
	ds_read_b128 v[228:231], v116 offset:8192
	v_exp_f32_e32 v27, v28
	v_exp_f32_e32 v28, v29
	v_exp_f32_e32 v29, v30
	v_exp_f32_e32 v30, v31
	v_exp_f32_e32 v31, v32
	v_exp_f32_e32 v32, v33
	v_exp_f32_e32 v33, v2
	v_add_f32_e32 v2, 0, v17
	v_add_f32_e32 v2, v18, v2
	s_waitcnt lgkmcnt(6)
	v_mfma_f32_32x32x16_bf16 v[50:65], v[200:203], v[82:85], v[50:65]
	v_add_f32_e32 v2, v19, v2
	v_add_f32_e32 v2, v20, v2
	v_add_f32_e32 v2, v21, v2
	v_add_f32_e32 v2, v22, v2
	v_add_f32_e32 v2, v23, v2
	v_add_f32_e32 v2, v24, v2
	v_add_f32_e32 v2, v25, v2
	v_add_f32_e32 v2, v26, v2
	v_add_f32_e32 v2, v27, v2
	v_add_f32_e32 v2, v28, v2
	v_mfma_f32_32x32x16_bf16 v[34:49], v[204:207], v[82:85], v[34:49]
	v_add_f32_e32 v2, v29, v2
	v_exp_f32_e32 v122, v3
	v_add_f32_e32 v2, v30, v2
	v_exp_f32_e32 v123, v4
	v_add_f32_e32 v2, v31, v2
	v_exp_f32_e32 v124, v5
	v_add_f32_e32 v2, v32, v2
	v_exp_f32_e32 v125, v6
	v_add_f32_e32 v2, v33, v2
	s_waitcnt lgkmcnt(4)
	v_mfma_f32_32x32x16_bf16 v[50:65], v[208:211], v[86:89], v[50:65]
	v_exp_f32_e32 v126, v7
	v_add_f32_e32 v2, v122, v2
	v_exp_f32_e32 v127, v8
	v_add_f32_e32 v2, v123, v2
	v_exp_f32_e32 v128, v9
	v_add_f32_e32 v2, v124, v2
	v_exp_f32_e32 v129, v10
	v_add_f32_e32 v2, v125, v2
	v_exp_f32_e32 v130, v11
	v_mfma_f32_32x32x16_bf16 v[34:49], v[212:215], v[86:89], v[34:49]
	v_add_f32_e32 v2, v126, v2
	v_exp_f32_e32 v131, v12
	v_add_f32_e32 v2, v127, v2
	v_exp_f32_e32 v132, v13
	v_add_f32_e32 v2, v128, v2
	v_mul_f32_e32 v119, 0x3e0293ee, v119
	v_exp_f32_e32 v133, v14
	v_add_f32_e32 v2, v129, v2
	v_exp_f32_e32 v119, v119
	v_exp_f32_e32 v134, v15
	s_waitcnt lgkmcnt(2)
; __device__ __forceinline__ void finishSM(f32x16& p0, f32x16& p1, float alpha, float& l_reg, bf16x8& pa0, bf16x8& pa1, bf16x8& pa2, bf16x8& pa3) {
; #pragma unroll
;   for (int r = 0; r < 16; ++r) p1[r] = __builtin_amdgcn_exp2f(p1[r]);
;   float ps = 0;
; #pragma unroll
;   for (int r = 0; r < 16; ++r) ps += p0[r];
; #pragma unroll
;   for (int r = 0; r < 16; ++r) ps += p1[r];
;   { auto rr = __builtin_amdgcn_permlane32_swap(__float_as_uint(ps), __float_as_uint(ps), false, false);
;     ps = __uint_as_float(rr[0]) + __uint_as_float(rr[1]); }
;   l_reg = l_reg * alpha + ps;
;     ...
;   PK4(p0, 0, pa0); PK4(p0, 8, pa1); PK4(p1, 0, pa2); PK4(p1, 8, pa3);
;     ...
; }
	v_mfma_f32_32x32x16_bf16 v[50:65], v[216:219], v[90:93], v[50:65]
	v_add_f32_e32 v2, v130, v2
	v_exp_f32_e32 v135, v16
	v_add_f32_e32 v2, v131, v2
	v_exp_f32_e32 v99, v99
	v_add_f32_e32 v2, v132, v2
	v_add_f32_e32 v2, v133, v2
	v_cndmask_b32_e64 v118, v119, 1.0, vcc
	v_add_f32_e32 v2, v134, v2
	v_add_f32_e32 v2, v135, v2
	v_mfma_f32_32x32x16_bf16 v[34:49], v[220:223], v[90:93], v[34:49]
	v_cmp_gt_f32_e32 vcc, 1.0, v118
	v_add_f32_e32 v119, v99, v2
	s_cmp_lg_u64 vcc, 0
	v_mov_b32_e32 v120, v119
	v_cvt_pk_bf16_f32 v2, v17, v18
	v_cvt_pk_bf16_f32 v3, v19, v20
	v_cvt_pk_bf16_f32 v4, v21, v22
	v_cvt_pk_bf16_f32 v5, v23, v24
	s_cselect_b64 s[50:51], -1, 0
	s_waitcnt lgkmcnt(0)
	v_mfma_f32_32x32x16_bf16 v[50:65], v[224:227], v[94:97], v[50:65]
	s_nop 0
	v_permlane32_swap_b32_e32 v119, v120
	v_permlane32_swap_b32_e32 v2, v4
	v_permlane32_swap_b32_e32 v3, v5
	v_cvt_pk_bf16_f32 v6, v25, v26
	v_cvt_pk_bf16_f32 v7, v27, v28
	v_cvt_pk_bf16_f32 v8, v29, v30
	v_cvt_pk_bf16_f32 v9, v31, v32
	v_cvt_pk_bf16_f32 v10, v33, v122
	v_cvt_pk_bf16_f32 v11, v123, v124
	v_mfma_f32_32x32x16_bf16 v[34:49], v[228:231], v[94:97], v[34:49]
	v_cvt_pk_bf16_f32 v12, v125, v126
	v_cvt_pk_bf16_f32 v13, v127, v128
	v_cvt_pk_bf16_f32 v14, v129, v130
	v_cvt_pk_bf16_f32 v15, v131, v132
	v_cvt_pk_bf16_f32 v16, v133, v134
	v_cvt_pk_bf16_f32 v17, v135, v99
	s_and_b64 s[74:75], s[50:51], s[0:1]
	v_permlane32_swap_b32_e32 v6, v8
	v_permlane32_swap_b32_e32 v7, v9
	v_permlane32_swap_b32_e32 v10, v12
	v_permlane32_swap_b32_e32 v11, v13
	v_permlane32_swap_b32_e32 v14, v16
	v_permlane32_swap_b32_e32 v15, v17
	ds_write_b128 v179, v[2:5]
	ds_write_b128 v179, v[6:9] offset:1024
	ds_write_b128 v179, v[10:13] offset:2048
	ds_write_b128 v179, v[14:17] offset:3072
	s_and_saveexec_b64 s[52:53], s[74:75]
	ds_write_b32 v117, v118
	s_or_b64 exec, exec, s[52:53]
	s_and_saveexec_b64 s[52:53], s[4:5]
	v_cndmask_b32_e64 v2, 0, 1.0, s[50:51]
	v_mov_b32_e32 v3, s65
	ds_write_b32 v3, v2 offset:128
	s_or_b64 exec, exec, s[52:53]
	s_waitcnt vmcnt(0)
	s_waitcnt lgkmcnt(0)
	s_barrier
	s_cmpk_lt_u32 s71, 0x7d
	s_cselect_b32 s8, s72, 0xfe000
	s_lshl_b64 s[84:85], s[8:9], 1
	s_add_u32 s84, s46, s84
	s_addc_u32 s85, s47, s85
	ds_read_b128 v[200:203], v100
	ds_read_b128 v[204:207], v100 offset:8192
	ds_read_b128 v[208:211], v101
	ds_read_b128 v[212:215], v101 offset:8192
	ds_read_b128 v[216:219], v102
	ds_read_b128 v[220:223], v102 offset:8192
	ds_read_b128 v[224:227], v103
	ds_read_b128 v[228:231], v103 offset:8192
	s_mov_b32 m0, s67
	s_nop 0
	global_load_lds_dwordx4 v0, s[84:85]
	s_mov_b32 m0, s68
	s_nop 0
	global_load_lds_dwordx4 v236, s[84:85]
	s_mov_b32 m0, s69
	s_nop 0
	global_load_lds_dwordx4 v237, s[84:85]
	s_mov_b32 m0, s70
	s_nop 0
	global_load_lds_dwordx4 v238, s[84:85]
	v_max_f32_e32 v99, v51, v51
	v_max_f32_e32 v122, v50, v50
	v_max_f32_e32 v99, v122, v99
	v_max3_f32 v99, v99, v52, v53
	v_max3_f32 v99, v99, v54, v55
	v_max3_f32 v99, v99, v56, v57
	v_max3_f32 v99, v99, v58, v59
	v_max3_f32 v99, v99, v60, v61
	v_max3_f32 v99, v99, v62, v63
	v_max3_f32 v99, v99, v64, v65
	s_waitcnt lgkmcnt(6)
	v_mfma_f32_32x32x16_bf16 v[18:33], v[200:203], v[66:69], 0
	v_max3_f32 v99, v99, v34, v35
	v_max3_f32 v99, v99, v36, v37
	v_max3_f32 v99, v99, v38, v39
	v_max3_f32 v99, v99, v40, v41
	v_max3_f32 v99, v99, v42, v43
	v_max3_f32 v99, v99, v44, v45
	v_max3_f32 v99, v99, v46, v47
	v_max3_f32 v99, v99, v48, v49
	v_mov_b32_e32 v122, v99
	v_mfma_f32_32x32x16_bf16 v[2:17], v[204:207], v[66:69], 0
	ds_read_b128 v[200:203], v104
	ds_read_b128 v[204:207], v104 offset:8192
	s_nop 1
	v_permlane32_swap_b32_e32 v99, v122
	v_max_f32_e32 v122, v122, v122
	v_max_f32_e32 v99, v99, v99
	v_max_f32_e32 v99, v99, v122
	v_sub_f32_e32 v122, v99, v121
	v_cmp_ge_f32_e32 vcc, s61, v122
	v_max_f32_e32 v123, v121, v121
	s_cmp_eq_u64 vcc, exec
	v_max_f32_e32 v123, v123, v99
	s_cselect_b64 vcc, -1, 0
	s_waitcnt lgkmcnt(6)
	v_mfma_f32_32x32x16_bf16 v[18:33], v[208:211], v[70:73], v[18:33]
	v_sub_f32_e32 v99, v121, v123
	v_cndmask_b32_e32 v121, v123, v121, vcc
	v_mul_f32_e32 v122, 0xbe0293ee, v121
	v_fmamk_f32 v50, v50, 0x3e0293ee, v122
	v_fmamk_f32 v51, v51, 0x3e0293ee, v122
	v_fmamk_f32 v52, v52, 0x3e0293ee, v122
	v_fmamk_f32 v53, v53, 0x3e0293ee, v122
	v_fmamk_f32 v54, v54, 0x3e0293ee, v122
	v_mfma_f32_32x32x16_bf16 v[2:17], v[212:215], v[70:73], v[2:17]
	ds_read_b128 v[208:211], v105
	ds_read_b128 v[212:215], v105 offset:8192
	v_fmamk_f32 v55, v55, 0x3e0293ee, v122
	v_fmamk_f32 v56, v56, 0x3e0293ee, v122
	v_fmamk_f32 v57, v57, 0x3e0293ee, v122
	v_fmamk_f32 v58, v58, 0x3e0293ee, v122
	v_fmamk_f32 v59, v59, 0x3e0293ee, v122
	v_fmamk_f32 v60, v60, 0x3e0293ee, v122
	v_fmamk_f32 v61, v61, 0x3e0293ee, v122
	v_fmamk_f32 v62, v62, 0x3e0293ee, v122
	v_fmamk_f32 v63, v63, 0x3e0293ee, v122
	s_waitcnt lgkmcnt(6)
; __device__ __forceinline__ void partialSM(f32x16& p0, f32x16& p1, float& m_reg, float& mn, float& alpha) {
;   constexpr float C = SCALE * L2E;
;   float pmax = p0[0];
; #pragma unroll
;   for (int r = 1; r < 16; ++r) pmax = fmaxf(pmax, p0[r]);
; #pragma unroll
;   for (int r = 0; r < 16; ++r) pmax = fmaxf(pmax, p1[r]);
;   { auto rr = __builtin_amdgcn_permlane32_swap(__float_as_uint(pmax), __float_as_uint(pmax), false, false);
;     pmax = fmaxf(__uint_as_float(rr[0]), __uint_as_float(rr[1])); }
;   if (__builtin_expect(__all(pmax - m_reg <= THR / SCALE), 1)) { mn = m_reg; alpha = 1.f; }
;   else { mn = fmaxf(m_reg, pmax); alpha = __builtin_amdgcn_exp2f((m_reg - mn) * C); m_reg = mn; }
;   float mnC = -mn * C;
; #pragma unroll
;   for (int r = 0; r < 16; ++r) p0[r] = fmaf(p0[r], C, mnC);
; #pragma unroll
;   for (int r = 0; r < 16; ++r) p1[r] = fmaf(p1[r], C, mnC);
; #pragma unroll
;   for (int r = 0; r < 16; ++r) p0[r] = __builtin_amdgcn_exp2f(p0[r]);
; }
; __device__ __forceinline__ void finishSM(f32x16& p0, f32x16& p1, float alpha, float& l_reg, bf16x8& pa0, bf16x8& pa1, bf16x8& pa2, bf16x8& pa3) {
; #pragma unroll
;   for (int r = 0; r < 16; ++r) p1[r] = __builtin_amdgcn_exp2f(p1[r]);
;   float ps = 0;
; #pragma unroll
;   for (int r = 0; r < 16; ++r) ps += p0[r];
; #pragma unroll
;   for (int r = 0; r < 16; ++r) ps += p1[r];
;   { auto rr = __builtin_amdgcn_permlane32_swap(__float_as_uint(ps), __float_as_uint(ps), false, false);
;     ps = __uint_as_float(rr[0]) + __uint_as_float(rr[1]); }
;   l_reg = l_reg * alpha + ps;
;     ...
;   PK4(p0, 0, pa0); PK4(p0, 8, pa1); PK4(p1, 0, pa2); PK4(p1, 8, pa3);
;     ...
; }
	v_mfma_f32_32x32x16_bf16 v[18:33], v[216:219], v[74:77], v[18:33]
	v_fmamk_f32 v64, v64, 0x3e0293ee, v122
	v_fmamk_f32 v65, v65, 0x3e0293ee, v122
	v_fmamk_f32 v34, v34, 0x3e0293ee, v122
	v_fmamk_f32 v35, v35, 0x3e0293ee, v122
	v_fmamk_f32 v36, v36, 0x3e0293ee, v122
	v_fmamk_f32 v37, v37, 0x3e0293ee, v122
	v_fmamk_f32 v38, v38, 0x3e0293ee, v122
	v_fmamk_f32 v39, v39, 0x3e0293ee, v122
	v_fmamk_f32 v40, v40, 0x3e0293ee, v122
	v_mfma_f32_32x32x16_bf16 v[2:17], v[220:223], v[74:77], v[2:17]
	ds_read_b128 v[216:219], v106
	ds_read_b128 v[220:223], v106 offset:8192
	v_fmamk_f32 v41, v41, 0x3e0293ee, v122
	v_fmamk_f32 v42, v42, 0x3e0293ee, v122
	v_fmamk_f32 v43, v43, 0x3e0293ee, v122
	v_fmamk_f32 v44, v44, 0x3e0293ee, v122
	v_fmamk_f32 v45, v45, 0x3e0293ee, v122
	v_fmamk_f32 v46, v46, 0x3e0293ee, v122
	v_fmamk_f32 v47, v47, 0x3e0293ee, v122
	v_fmamk_f32 v48, v48, 0x3e0293ee, v122
	v_fmac_f32_e32 v122, 0x3e0293ee, v49
	v_exp_f32_e32 v49, v50
	s_waitcnt lgkmcnt(6)
	v_mfma_f32_32x32x16_bf16 v[18:33], v[224:227], v[78:81], v[18:33]
	v_exp_f32_e32 v50, v51
	v_exp_f32_e32 v51, v52
	v_exp_f32_e32 v52, v53
	v_exp_f32_e32 v53, v54
	v_exp_f32_e32 v54, v55
	v_exp_f32_e32 v55, v56
	v_exp_f32_e32 v56, v57
	v_exp_f32_e32 v57, v58
	v_exp_f32_e32 v58, v59
	v_mfma_f32_32x32x16_bf16 v[2:17], v[228:231], v[78:81], v[2:17]
	ds_read_b128 v[224:227], v107
	ds_read_b128 v[228:231], v107 offset:8192
	v_exp_f32_e32 v59, v60
	v_exp_f32_e32 v60, v61
	v_exp_f32_e32 v61, v62
	v_exp_f32_e32 v62, v63
	v_exp_f32_e32 v63, v64
	v_exp_f32_e32 v64, v65
	v_exp_f32_e32 v65, v34
	v_add_f32_e32 v34, 0, v49
	v_add_f32_e32 v34, v50, v34
	s_waitcnt lgkmcnt(6)
	v_mfma_f32_32x32x16_bf16 v[18:33], v[200:203], v[82:85], v[18:33]
	v_add_f32_e32 v34, v51, v34
	v_add_f32_e32 v34, v52, v34
	v_add_f32_e32 v34, v53, v34
	v_add_f32_e32 v34, v54, v34
	v_add_f32_e32 v34, v55, v34
	v_add_f32_e32 v34, v56, v34
	v_add_f32_e32 v34, v57, v34
	v_add_f32_e32 v34, v58, v34
	v_add_f32_e32 v34, v59, v34
	v_add_f32_e32 v34, v60, v34
	v_mfma_f32_32x32x16_bf16 v[2:17], v[204:207], v[82:85], v[2:17]
	v_add_f32_e32 v34, v61, v34
	v_exp_f32_e32 v123, v35
	v_add_f32_e32 v34, v62, v34
	v_exp_f32_e32 v124, v36
	v_add_f32_e32 v34, v63, v34
	v_exp_f32_e32 v125, v37
	v_add_f32_e32 v34, v64, v34
	v_exp_f32_e32 v126, v38
	v_add_f32_e32 v34, v65, v34
	s_waitcnt lgkmcnt(4)
	v_mfma_f32_32x32x16_bf16 v[18:33], v[208:211], v[86:89], v[18:33]
	v_exp_f32_e32 v127, v39
	v_add_f32_e32 v34, v123, v34
	v_exp_f32_e32 v128, v40
	v_add_f32_e32 v34, v124, v34
	v_exp_f32_e32 v129, v41
	v_add_f32_e32 v34, v125, v34
	v_exp_f32_e32 v130, v42
	v_add_f32_e32 v34, v126, v34
	v_exp_f32_e32 v131, v43
	v_mfma_f32_32x32x16_bf16 v[2:17], v[212:215], v[86:89], v[2:17]
	v_add_f32_e32 v34, v127, v34
	v_exp_f32_e32 v132, v44
	v_add_f32_e32 v34, v128, v34
	v_exp_f32_e32 v133, v45
	v_add_f32_e32 v34, v129, v34
	v_mul_f32_e32 v99, 0x3e0293ee, v99
	v_exp_f32_e32 v134, v46
	v_add_f32_e32 v34, v130, v34
	v_exp_f32_e32 v99, v99
	v_exp_f32_e32 v135, v47
	s_waitcnt lgkmcnt(2)
	v_mfma_f32_32x32x16_bf16 v[18:33], v[216:219], v[90:93], v[18:33]
	v_add_f32_e32 v34, v131, v34
	v_exp_f32_e32 v136, v48
	v_add_f32_e32 v34, v132, v34
	v_exp_f32_e32 v122, v122
	v_add_f32_e32 v34, v133, v34
	v_add_f32_e32 v34, v134, v34
	v_cndmask_b32_e64 v99, v99, 1.0, vcc
	v_add_f32_e32 v34, v135, v34
	v_add_f32_e32 v34, v136, v34
	v_mfma_f32_32x32x16_bf16 v[2:17], v[220:223], v[90:93], v[2:17]
	v_cmp_gt_f32_e32 vcc, 1.0, v99
	v_add_f32_e32 v34, v122, v34
	s_cmp_lg_u64 vcc, 0
	v_mov_b32_e32 v35, v34
	v_cvt_pk_bf16_f32 v36, v49, v50
	v_cvt_pk_bf16_f32 v37, v51, v52
	v_cvt_pk_bf16_f32 v38, v53, v54
	v_cvt_pk_bf16_f32 v39, v55, v56
	s_cselect_b64 s[50:51], -1, 0
	s_waitcnt lgkmcnt(0)
	v_mfma_f32_32x32x16_bf16 v[18:33], v[224:227], v[94:97], v[18:33]
	s_nop 0
	v_permlane32_swap_b32_e32 v34, v35
	v_permlane32_swap_b32_e32 v36, v38
	v_permlane32_swap_b32_e32 v37, v39
	v_cvt_pk_bf16_f32 v40, v57, v58
	v_cvt_pk_bf16_f32 v41, v59, v60
	v_cvt_pk_bf16_f32 v42, v61, v62
	v_cvt_pk_bf16_f32 v43, v63, v64
	v_cvt_pk_bf16_f32 v44, v65, v123
	v_cvt_pk_bf16_f32 v45, v124, v125
	v_mfma_f32_32x32x16_bf16 v[2:17], v[228:231], v[94:97], v[2:17]
	v_cvt_pk_bf16_f32 v46, v126, v127
	v_cvt_pk_bf16_f32 v47, v128, v129
	v_cvt_pk_bf16_f32 v48, v130, v131
	v_cvt_pk_bf16_f32 v49, v132, v133
	v_cvt_pk_bf16_f32 v50, v134, v135
	v_cvt_pk_bf16_f32 v51, v136, v122
	s_and_b64 s[74:75], s[50:51], s[0:1]
	v_permlane32_swap_b32_e32 v40, v42
	v_permlane32_swap_b32_e32 v41, v43
	v_permlane32_swap_b32_e32 v44, v46
	v_permlane32_swap_b32_e32 v45, v47
	v_permlane32_swap_b32_e32 v48, v50
	v_permlane32_swap_b32_e32 v49, v51
	ds_write_b128 v179, v[36:39] offset:16384
	ds_write_b128 v179, v[40:43] offset:17408
	ds_write_b128 v179, v[44:47] offset:18432
	ds_write_b128 v179, v[48:51] offset:19456
	s_and_saveexec_b64 s[52:53], s[74:75]
	ds_write_b32 v117, v99 offset:1024
	s_or_b64 exec, exec, s[52:53]
	s_and_saveexec_b64 s[52:53], s[4:5]
	s_cbranch_execz .LBB0_507
	v_cndmask_b32_e64 v36, 0, 1.0, s[50:51]
	v_mov_b32_e32 v37, s65
	ds_write_b32 v37, v36 offset:1152
	s_branch .LBB0_507
